# v59 + attention steady loop: removed NaN-canonicalising max(x,x) and +0 adds (8 VALU per 2 tiles)
# baseline (speedup 1.0000x reference)
.LBB0_564:
	v_add_u32_e32 v0, s15, v218
	ds_read_b64_tr_b16 v[176:177], v0 offset:24576
	ds_read_b64_tr_b16 v[178:179], v0 offset:25088
	s_waitcnt lgkmcnt(9)
	v_mfma_f32_32x32x16_bf16 v[64:79], v[172:175], v[124:127], v[64:79]
	v_add_f32_e32 v2, v96, v97
	v_add_f32_e32 v2, v98, v2
	v_add_f32_e32 v2, v99, v2
	v_add_f32_e32 v2, v100, v2
	v_add_f32_e32 v2, v101, v2
	v_cvt_pk_bf16_f32 v140, v96, v97
	v_cvt_pk_bf16_f32 v141, v98, v99
	ds_read_b64_tr_b16 v[172:173], v0 offset:28672
	ds_read_b64_tr_b16 v[174:175], v0 offset:29184
	s_waitcnt lgkmcnt(10)
	v_mfma_f32_32x32x16_bf16 v[48:63], v[168:171], v[124:127], v[48:63]
	v_add_f32_e32 v2, v102, v2
	v_add_f32_e32 v2, v103, v2
	v_add_f32_e32 v2, v104, v2
	v_add_f32_e32 v2, v105, v2
	v_cvt_pk_bf16_f32 v142, v100, v101
	v_cvt_pk_bf16_f32 v143, v102, v103
	ds_read_b64_tr_b16 v[10:11], v0 offset:25600
	ds_read_b64_tr_b16 v[12:13], v0 offset:26112
	s_waitcnt lgkmcnt(11)
	v_mfma_f32_32x32x16_bf16 v[64:79], v[164:167], v[120:123], v[64:79]
	v_add_f32_e32 v2, v106, v2
	v_add_f32_e32 v2, v107, v2
	v_add_f32_e32 v2, v108, v2
	v_add_f32_e32 v2, v109, v2
	v_cvt_pk_bf16_f32 v136, v104, v105
	v_cvt_pk_bf16_f32 v137, v106, v107
	ds_read_b64_tr_b16 v[6:7], v0 offset:29696
	ds_read_b64_tr_b16 v[8:9], v0 offset:30208
	s_waitcnt lgkmcnt(12)
	v_mfma_f32_32x32x16_bf16 v[48:63], v[160:163], v[120:123], v[48:63]
	v_add_f32_e32 v2, v110, v2
	v_add_f32_e32 v2, v111, v2
	v_add_f32_e32 v2, v80, v2
	v_add_f32_e32 v14, v81, v2
	v_cvt_pk_bf16_f32 v138, v108, v109
	v_cvt_pk_bf16_f32 v139, v110, v111
	ds_read_b64_tr_b16 v[2:3], v0 offset:26624
	ds_read_b64_tr_b16 v[4:5], v0 offset:27136
	s_waitcnt lgkmcnt(13)
	v_mfma_f32_32x32x16_bf16 v[64:79], v[156:159], v[116:119], v[64:79]
	v_add_f32_e32 v14, v82, v14
	v_add_f32_e32 v14, v83, v14
	v_add_f32_e32 v14, v84, v14
	v_add_f32_e32 v14, v85, v14
	v_cvt_pk_bf16_f32 v132, v80, v81
	v_cvt_pk_bf16_f32 v133, v82, v83
	ds_read_b64_tr_b16 v[100:101], v0 offset:30720
	ds_read_b64_tr_b16 v[102:103], v0 offset:31232
	s_waitcnt lgkmcnt(14)
	v_mfma_f32_32x32x16_bf16 v[48:63], v[152:155], v[116:119], v[48:63]
	v_add_f32_e32 v14, v86, v14
	v_add_f32_e32 v14, v87, v14
	v_add_f32_e32 v14, v88, v14
	v_add_f32_e32 v14, v89, v14
	v_cvt_pk_bf16_f32 v134, v84, v85
	v_cvt_pk_bf16_f32 v135, v86, v87
	ds_read_b64_tr_b16 v[96:97], v0 offset:27648
	ds_read_b64_tr_b16 v[98:99], v0 offset:28160
	s_waitcnt lgkmcnt(14)
	v_mfma_f32_32x32x16_bf16 v[64:79], v[148:151], v[112:115], v[64:79]
	v_add_f32_e32 v14, v90, v14
	v_add_f32_e32 v14, v91, v14
	v_add_f32_e32 v14, v92, v14
	v_add_f32_e32 v14, v93, v14
	v_cvt_pk_bf16_f32 v128, v88, v89
	v_cvt_pk_bf16_f32 v129, v90, v91
	ds_read_b64_tr_b16 v[84:85], v0 offset:31744
	ds_read_b64_tr_b16 v[86:87], v0 offset:32256
	v_mfma_f32_32x32x16_bf16 v[48:63], v[144:147], v[112:115], v[48:63]
	v_add_f32_e32 v0, v94, v14
	v_add_f32_e32 v0, v95, v0
	s_nop 0
	v_cvt_pk_bf16_f32 v130, v92, v93
	v_cvt_pk_bf16_f32 v131, v94, v95
	v_lshl_add_u64 v[14:15], v[186:187], 0, s[58:59]
	s_add_i32 s15, s14, s83
	s_mov_b32 s33, m0
	s_mov_b32 m0, s15
	s_nop 0
	global_load_lds_dwordx4 v[14:15], off
	s_mov_b32 m0, s33
	v_lshl_add_u64 v[14:15], v[184:185], 0, s[58:59]
	s_add_i32 s15, s20, s84
	s_mov_b32 s33, m0
	s_mov_b32 m0, s15
	s_nop 0
	global_load_lds_dwordx4 v[14:15], off
	s_mov_b32 m0, s33
	s_nop 1
	v_max_f32_e32 v14, v64, v65
	v_max3_f32 v15, v66, v67, v49
	v_max3_f32 v14, v14, v48, v50
	v_max3_f32 v14, v14, v51, v68
	v_max3_f32 v15, v15, v70, v71
	v_max3_f32 v14, v14, v69, v52
	v_max3_f32 v15, v15, v54, v55
	v_max3_f32 v14, v14, v53, v72
	v_max3_f32 v15, v15, v74, v75
	v_max3_f32 v14, v14, v73, v56
	v_max3_f32 v15, v15, v58, v59
	v_max3_f32 v14, v14, v57, v76
	v_max3_f32 v15, v15, v78, v79
	v_max3_f32 v14, v14, v77, v60
	v_max3_f32 v15, v15, v62, v63
	v_max3_f32 v14, v14, v61, v15
	v_mov_b32_e32 v15, v14
	s_nop 1
	v_permlane32_swap_b32_e32 v14, v15
	v_max_f32_e32 v14, v14, v15
	v_cmp_lt_f32_e32 vcc, s72, v14
	s_cmp_lg_u64 vcc, 0
	v_add_f32_e32 v0, v220, v0
	s_cselect_b64 s[60:61], -1, 0
	s_cbranch_vccnz .LBB0_572

.LBB0_567:
	s_add_i32 s15, s20, 0x2000
	s_cmpk_lg_i32 s20, 0x4000
	s_waitcnt lgkmcnt(10)
	v_sub_f32_e32 v111, v219, v111
	v_sub_f32_e32 v110, v219, v110
	v_sub_f32_e32 v109, v219, v109
	v_sub_f32_e32 v108, v219, v108
	v_sub_f32_e32 v107, v219, v107
	v_sub_f32_e32 v106, v219, v106
	v_sub_f32_e32 v105, v219, v105
	v_sub_f32_e32 v104, v219, v104
	v_sub_f32_e32 v103, v219, v183
	v_sub_f32_e32 v102, v219, v182
	v_sub_f32_e32 v101, v219, v181
	v_sub_f32_e32 v100, v219, v180
	v_sub_f32_e32 v99, v219, v171
	v_sub_f32_e32 v98, v219, v170
	v_sub_f32_e32 v97, v219, v169
	v_sub_f32_e32 v96, v219, v168
	s_waitcnt lgkmcnt(8)
	v_sub_f32_e32 v95, v219, v95
	v_sub_f32_e32 v94, v219, v94
	v_sub_f32_e32 v93, v219, v93
	v_sub_f32_e32 v92, v219, v92
	v_sub_f32_e32 v91, v219, v91
	v_sub_f32_e32 v90, v219, v90
	v_sub_f32_e32 v89, v219, v89
	v_sub_f32_e32 v88, v219, v88
	v_sub_f32_e32 v87, v219, v163
	v_sub_f32_e32 v86, v219, v162
	v_sub_f32_e32 v85, v219, v161
	v_sub_f32_e32 v84, v219, v160
	v_sub_f32_e32 v83, v219, v83
	v_sub_f32_e32 v82, v219, v82
	v_sub_f32_e32 v81, v219, v81
	v_sub_f32_e32 v80, v219, v80
	s_cselect_b32 s87, s15, 0
	v_add_u32_e32 v14, s14, v218
	ds_read_b64_tr_b16 v[168:169], v14 offset:24576
	ds_read_b64_tr_b16 v[170:171], v14 offset:25088
	s_waitcnt lgkmcnt(9)
	v_mfma_f32_32x32x16_bf16 v[96:111], v[164:167], v[124:127], v[96:111]
	v_add_f32_e32 v15, v64, v65
	v_add_f32_e32 v15, v66, v15
	v_add_f32_e32 v15, v67, v15
	v_add_f32_e32 v15, v68, v15
	v_add_f32_e32 v15, v69, v15
	v_cvt_pk_bf16_f32 v140, v64, v65
	v_cvt_pk_bf16_f32 v141, v66, v67
	ds_read_b64_tr_b16 v[160:161], v14 offset:28672
	ds_read_b64_tr_b16 v[162:163], v14 offset:29184
	s_waitcnt lgkmcnt(10)
	v_mfma_f32_32x32x16_bf16 v[80:95], v[152:155], v[124:127], v[80:95]
	v_add_f32_e32 v15, v70, v15
	v_add_f32_e32 v15, v71, v15
	v_add_f32_e32 v15, v72, v15
	v_add_f32_e32 v15, v73, v15
	v_cvt_pk_bf16_f32 v142, v68, v69
	v_cvt_pk_bf16_f32 v143, v70, v71
	ds_read_b64_tr_b16 v[152:153], v14 offset:25600
	ds_read_b64_tr_b16 v[154:155], v14 offset:26112
	s_waitcnt lgkmcnt(11)
	v_mfma_f32_32x32x16_bf16 v[96:111], v[156:159], v[120:123], v[96:111]
	v_add_f32_e32 v15, v74, v15
	v_add_f32_e32 v15, v75, v15
	v_add_f32_e32 v15, v76, v15
	v_add_f32_e32 v15, v77, v15
	v_cvt_pk_bf16_f32 v136, v72, v73
	v_cvt_pk_bf16_f32 v137, v74, v75
	ds_read_b64_tr_b16 v[72:73], v14 offset:29696
	ds_read_b64_tr_b16 v[74:75], v14 offset:30208
	s_waitcnt lgkmcnt(12)
	v_mfma_f32_32x32x16_bf16 v[80:95], v[144:147], v[120:123], v[80:95]
	v_add_f32_e32 v15, v78, v15
	v_add_f32_e32 v15, v79, v15
	v_add_f32_e32 v15, v48, v15
	v_add_f32_e32 v15, v49, v15
	v_cvt_pk_bf16_f32 v138, v76, v77
	v_cvt_pk_bf16_f32 v139, v78, v79
	ds_read_b64_tr_b16 v[68:69], v14 offset:26624
	ds_read_b64_tr_b16 v[70:71], v14 offset:27136
	s_waitcnt lgkmcnt(13)
	v_mfma_f32_32x32x16_bf16 v[96:111], v[148:151], v[116:119], v[96:111]
	v_add_f32_e32 v15, v50, v15
	v_add_f32_e32 v15, v51, v15
	v_add_f32_e32 v15, v52, v15
	v_add_f32_e32 v15, v53, v15
	v_cvt_pk_bf16_f32 v132, v48, v49
	v_cvt_pk_bf16_f32 v133, v50, v51
	ds_read_b64_tr_b16 v[64:65], v14 offset:30720
	ds_read_b64_tr_b16 v[66:67], v14 offset:31232
	s_waitcnt lgkmcnt(14)
	v_mfma_f32_32x32x16_bf16 v[80:95], v[6:9], v[116:119], v[80:95]
	v_add_f32_e32 v15, v54, v15
	v_add_f32_e32 v15, v55, v15
	v_add_f32_e32 v15, v56, v15
	v_add_f32_e32 v15, v57, v15
	v_cvt_pk_bf16_f32 v134, v52, v53
	v_cvt_pk_bf16_f32 v135, v54, v55
	ds_read_b64_tr_b16 v[48:49], v14 offset:27648
	ds_read_b64_tr_b16 v[50:51], v14 offset:28160
	s_waitcnt lgkmcnt(14)
	v_mfma_f32_32x32x16_bf16 v[96:111], v[10:13], v[112:115], v[96:111]
	v_add_f32_e32 v6, v58, v15
	v_add_f32_e32 v6, v59, v6
	v_add_f32_e32 v6, v60, v6
	v_add_f32_e32 v6, v61, v6
	v_cvt_pk_bf16_f32 v128, v56, v57
	v_cvt_pk_bf16_f32 v129, v58, v59
	ds_read_b64_tr_b16 v[10:11], v14 offset:31744
	ds_read_b64_tr_b16 v[12:13], v14 offset:32256
	v_mfma_f32_32x32x16_bf16 v[80:95], v[2:5], v[112:115], v[80:95]
	v_add_f32_e32 v6, v62, v6
	v_add_f32_e32 v6, v63, v6
	s_nop 0
	v_cvt_pk_bf16_f32 v130, v60, v61
	v_cvt_pk_bf16_f32 v131, v62, v63
	v_max_f32_e32 v2, v96, v97
	s_nop 5
	v_max3_f32 v3, v98, v99, v81
	v_max3_f32 v2, v2, v80, v82
	v_max3_f32 v2, v2, v83, v100
	v_max3_f32 v3, v3, v102, v103
	v_max3_f32 v2, v2, v101, v84
	v_max3_f32 v3, v3, v86, v87
	v_max3_f32 v2, v2, v85, v104
	v_max3_f32 v3, v3, v106, v107
	v_max3_f32 v2, v2, v105, v88
	v_max3_f32 v3, v3, v90, v91
	v_max3_f32 v2, v2, v89, v108
	v_max3_f32 v3, v3, v110, v111
	v_max3_f32 v2, v2, v109, v92
	v_max3_f32 v3, v3, v94, v95
	v_add_f32_e32 v220, v0, v6
	v_max3_f32 v0, v2, v93, v3
	v_mov_b32_e32 v2, v0
	s_nop 1
	v_permlane32_swap_b32_e32 v0, v2
	s_add_i32 s14, s20, s83
	s_mov_b32 s15, m0
	s_mov_b32 m0, s14
	s_nop 0
	global_load_lds_dwordx4 v[186:187], off
	s_mov_b32 m0, s15
	v_max_f32_e32 v0, v0, v2
	s_add_i32 s14, s87, s84
	s_mov_b32 s15, m0
	s_mov_b32 m0, s14
	s_nop 0
	global_load_lds_dwordx4 v[184:185], off
	s_mov_b32 m0, s15
	v_cmp_lt_f32_e32 vcc, s72, v0
	s_cmp_lg_u64 vcc, 0
	s_cselect_b64 s[60:61], -1, 0
	s_cbranch_vccnz .LBB0_575
